# branch-projection epilogues: four steps of gate/T loads in flight, in-place unpack/fma, stores never waited
# baseline (speedup 1.0000x reference)
; #define EPI_FENCE() asm volatile("" ::: "memory")
;     __device__ __forceinline__ void operator()(const Acc& acc, const Unit& u, int wr, int wc, int fr, int fq) const {
;         const int row0 = u.pm * BM + wr * 64 + fr, col0 = u.pn * BM + wc * 32 + 8 * fq;
; #pragma unroll
;         for (int ai = 0; ai < 2; ++ai)
; #pragma unroll
;             for (int m = 0; m < 4; ++m) { const int row = row0 + ai * HALF + m * 16;
; #pragma unroll
;                 for (int bj = 0; bj < 2; ++bj) {
;                     const u32x4 gw = *(const u32x4*)(QG + (size_t)row * QGW + gcol0 + col0 + bj * HALF);
;                     float gt[8]; unpack8(gw, gt);
;                     bf16_t* tp = T + (size_t)row * DM + col0 + bj * HALF;
;                     float o[8];
;                     const f32x4 v0 = acc[ai][bj][m][0], v1 = acc[ai][bj][m][1];
; #pragma unroll
;                     for (int j = 0; j < 4; ++j) { o[j] = gt[j] * v0[j]; o[4 + j] = gt[4 + j] * v1[j]; }
;                     if (MODE == 1) { const u32x4 tw = *(const u32x4*)tp; float tv[8]; unpack8(tw, tv);
; #pragma unroll
;                         for (int j = 0; j < 8; ++j) o[j] += tv[j]; }
;                     *(u32x4*)tp = pack8(o); }
;                 EPI_FENCE(); }
;     }
.LBB0_728:
	v_lshl_or_b32 v144, s60, 8, v169
	v_lshl_add_u32 v146, s59, 8, v161
	v_ashrrev_i32_e32 v145, 31, v144
	v_mov_b64_e32 v[148:149], s[12:13]
	v_mad_i64_i32 v[174:175], s[0:1], v146, s56, v[148:149]
	v_lshlrev_b64 v[144:145], 1, v[144:145]
	v_lshl_add_u64 v[178:179], v[174:175], 0, v[144:145]
	v_add_co_u32_e32 v174, vcc, 0x1000, v178
	s_nop 1
	v_addc_co_u32_e32 v175, vcc, 0, v179, vcc
	v_ashrrev_i32_e32 v147, 31, v146
	v_lshlrev_b64 v[232:233], 12, v[146:147]
	v_lshl_add_u64 v[232:233], s[10:11], 0, v[232:233]
	v_lshl_add_u64 v[232:233], v[232:233], 0, v[144:145]
	s_mov_b32 s99, 0
	global_load_dwordx4 v[182:185], v[174:175], off offset:2048
	global_load_dwordx4 v[186:189], v[174:175], off offset:2304
	s_mov_b32 s98, 0x38000
	v_lshl_add_u64 v[174:175], v[174:175], 0, s[98:99]
	global_load_dwordx4 v[190:193], v[174:175], off offset:2048
	global_load_dwordx4 v[194:197], v[174:175], off offset:2304
	s_mov_b32 s98, 0x38000
	v_lshl_add_u64 v[174:175], v[174:175], 0, s[98:99]
	s_waitcnt vmcnt(3)
	v_lshlrev_b32_e32 v198, 16, v182
	v_and_b32_e32 v182, 0xffff0000, v182
	v_lshlrev_b32_e32 v199, 16, v183
	v_and_b32_e32 v183, 0xffff0000, v183
	v_lshlrev_b32_e32 v200, 16, v184
	v_and_b32_e32 v184, 0xffff0000, v184
	v_lshlrev_b32_e32 v201, 16, v185
	v_and_b32_e32 v185, 0xffff0000, v185
	v_mul_f32_e32 v124, v124, v198
	v_mul_f32_e32 v125, v125, v182
	v_mul_f32_e32 v126, v126, v199
	v_mul_f32_e32 v127, v127, v183
	v_mul_f32_e32 v120, v120, v200
	v_mul_f32_e32 v121, v121, v184
	v_mul_f32_e32 v122, v122, v201
	v_mul_f32_e32 v123, v123, v185
	v_cvt_pk_bf16_f32 v182, v124, v125
	v_cvt_pk_bf16_f32 v183, v126, v127
	v_cvt_pk_bf16_f32 v184, v120, v121
	v_cvt_pk_bf16_f32 v185, v122, v123
	global_store_dwordx4 v[232:233], v[182:185], off
	s_nop 0
	global_load_dwordx4 v[182:185], v[174:175], off offset:2048
	s_waitcnt vmcnt(4)
	v_lshlrev_b32_e32 v198, 16, v186
	v_and_b32_e32 v186, 0xffff0000, v186
	v_lshlrev_b32_e32 v199, 16, v187
	v_and_b32_e32 v187, 0xffff0000, v187
	v_lshlrev_b32_e32 v200, 16, v188
	v_and_b32_e32 v188, 0xffff0000, v188
	v_lshlrev_b32_e32 v201, 16, v189
	v_and_b32_e32 v189, 0xffff0000, v189
	v_mul_f32_e32 v116, v116, v198
	v_mul_f32_e32 v117, v117, v186
	v_mul_f32_e32 v118, v118, v199
	v_mul_f32_e32 v119, v119, v187
	v_mul_f32_e32 v108, v108, v200
	v_mul_f32_e32 v109, v109, v188
	v_mul_f32_e32 v110, v110, v201
	v_mul_f32_e32 v111, v111, v189
	v_cvt_pk_bf16_f32 v186, v116, v117
	v_cvt_pk_bf16_f32 v187, v118, v119
	v_cvt_pk_bf16_f32 v188, v108, v109
	v_cvt_pk_bf16_f32 v189, v110, v111
	global_store_dwordx4 v[232:233], v[186:189], off offset:256
	s_mov_b32 s98, 0x10000
	v_lshl_add_u64 v[232:233], v[232:233], 0, s[98:99]
	s_nop 0
	global_load_dwordx4 v[186:189], v[174:175], off offset:2304
	s_mov_b32 s98, 0x38000
	v_lshl_add_u64 v[174:175], v[174:175], 0, s[98:99]
	s_waitcnt vmcnt(5)
	v_lshlrev_b32_e32 v198, 16, v190
	v_and_b32_e32 v190, 0xffff0000, v190
	v_lshlrev_b32_e32 v199, 16, v191
	v_and_b32_e32 v191, 0xffff0000, v191
	v_lshlrev_b32_e32 v200, 16, v192
	v_and_b32_e32 v192, 0xffff0000, v192
	v_lshlrev_b32_e32 v201, 16, v193
	v_and_b32_e32 v193, 0xffff0000, v193
	v_mul_f32_e32 v112, v112, v198
	v_mul_f32_e32 v113, v113, v190
	v_mul_f32_e32 v114, v114, v199
	v_mul_f32_e32 v115, v115, v191
	v_mul_f32_e32 v104, v104, v200
	v_mul_f32_e32 v105, v105, v192
	v_mul_f32_e32 v106, v106, v201
	v_mul_f32_e32 v107, v107, v193
	v_cvt_pk_bf16_f32 v190, v112, v113
	v_cvt_pk_bf16_f32 v191, v114, v115
	v_cvt_pk_bf16_f32 v192, v104, v105
	v_cvt_pk_bf16_f32 v193, v106, v107
	global_store_dwordx4 v[232:233], v[190:193], off
	s_nop 0
	global_load_dwordx4 v[190:193], v[174:175], off offset:2048
	s_waitcnt vmcnt(6)
	v_lshlrev_b32_e32 v198, 16, v194
	v_and_b32_e32 v194, 0xffff0000, v194
	v_lshlrev_b32_e32 v199, 16, v195
	v_and_b32_e32 v195, 0xffff0000, v195
	v_lshlrev_b32_e32 v200, 16, v196
	v_and_b32_e32 v196, 0xffff0000, v196
	v_lshlrev_b32_e32 v201, 16, v197
	v_and_b32_e32 v197, 0xffff0000, v197
	v_mul_f32_e32 v100, v100, v198
	v_mul_f32_e32 v101, v101, v194
	v_mul_f32_e32 v102, v102, v199
	v_mul_f32_e32 v103, v103, v195
	v_mul_f32_e32 v92, v92, v200
	v_mul_f32_e32 v93, v93, v196
	v_mul_f32_e32 v94, v94, v201
	v_mul_f32_e32 v95, v95, v197
	v_cvt_pk_bf16_f32 v194, v100, v101
	v_cvt_pk_bf16_f32 v195, v102, v103
	v_cvt_pk_bf16_f32 v196, v92, v93
	v_cvt_pk_bf16_f32 v197, v94, v95
	global_store_dwordx4 v[232:233], v[194:197], off offset:256
	s_mov_b32 s98, 0x10000
	v_lshl_add_u64 v[232:233], v[232:233], 0, s[98:99]
	s_nop 0
	global_load_dwordx4 v[194:197], v[174:175], off offset:2304
	s_mov_b32 s98, 0x118000
	v_lshl_add_u64 v[174:175], v[174:175], 0, s[98:99]
	s_waitcnt vmcnt(6)
	v_lshlrev_b32_e32 v198, 16, v182
	v_and_b32_e32 v182, 0xffff0000, v182
	v_lshlrev_b32_e32 v199, 16, v183
	v_and_b32_e32 v183, 0xffff0000, v183
	v_lshlrev_b32_e32 v200, 16, v184
	v_and_b32_e32 v184, 0xffff0000, v184
	v_lshlrev_b32_e32 v201, 16, v185
	v_and_b32_e32 v185, 0xffff0000, v185
	v_mul_f32_e32 v96, v96, v198
	v_mul_f32_e32 v97, v97, v182
	v_mul_f32_e32 v98, v98, v199
	v_mul_f32_e32 v99, v99, v183
	v_mul_f32_e32 v88, v88, v200
	v_mul_f32_e32 v89, v89, v184
	v_mul_f32_e32 v90, v90, v201
	v_mul_f32_e32 v91, v91, v185
	v_cvt_pk_bf16_f32 v182, v96, v97
	v_cvt_pk_bf16_f32 v183, v98, v99
	v_cvt_pk_bf16_f32 v184, v88, v89
	v_cvt_pk_bf16_f32 v185, v90, v91
	global_store_dwordx4 v[232:233], v[182:185], off
	s_nop 0
	global_load_dwordx4 v[182:185], v[174:175], off offset:2048
	s_waitcnt vmcnt(6)
; #define EPI_FENCE() asm volatile("" ::: "memory")
;     __device__ __forceinline__ void operator()(const Acc& acc, const Unit& u, int wr, int wc, int fr, int fq) const {
;         const int row0 = u.pm * BM + wr * 64 + fr, col0 = u.pn * BM + wc * 32 + 8 * fq;
; #pragma unroll
;         for (int ai = 0; ai < 2; ++ai)
; #pragma unroll
;             for (int m = 0; m < 4; ++m) { const int row = row0 + ai * HALF + m * 16;
; #pragma unroll
;                 for (int bj = 0; bj < 2; ++bj) {
;                     const u32x4 gw = *(const u32x4*)(QG + (size_t)row * QGW + gcol0 + col0 + bj * HALF);
;                     float gt[8]; unpack8(gw, gt);
;                     bf16_t* tp = T + (size_t)row * DM + col0 + bj * HALF;
;                     float o[8];
;                     const f32x4 v0 = acc[ai][bj][m][0], v1 = acc[ai][bj][m][1];
; #pragma unroll
;                     for (int j = 0; j < 4; ++j) { o[j] = gt[j] * v0[j]; o[4 + j] = gt[4 + j] * v1[j]; }
;                     if (MODE == 1) { const u32x4 tw = *(const u32x4*)tp; float tv[8]; unpack8(tw, tv);
; #pragma unroll
;                         for (int j = 0; j < 8; ++j) o[j] += tv[j]; }
;                     *(u32x4*)tp = pack8(o); }
;                 EPI_FENCE(); }
;     }
	v_lshlrev_b32_e32 v198, 16, v186
	v_and_b32_e32 v186, 0xffff0000, v186
	v_lshlrev_b32_e32 v199, 16, v187
	v_and_b32_e32 v187, 0xffff0000, v187
	v_lshlrev_b32_e32 v200, 16, v188
	v_and_b32_e32 v188, 0xffff0000, v188
	v_lshlrev_b32_e32 v201, 16, v189
	v_and_b32_e32 v189, 0xffff0000, v189
	v_mul_f32_e32 v84, v84, v198
	v_mul_f32_e32 v85, v85, v186
	v_mul_f32_e32 v86, v86, v199
	v_mul_f32_e32 v87, v87, v187
	v_mul_f32_e32 v76, v76, v200
	v_mul_f32_e32 v77, v77, v188
	v_mul_f32_e32 v78, v78, v201
	v_mul_f32_e32 v79, v79, v189
	v_cvt_pk_bf16_f32 v186, v84, v85
	v_cvt_pk_bf16_f32 v187, v86, v87
	v_cvt_pk_bf16_f32 v188, v76, v77
	v_cvt_pk_bf16_f32 v189, v78, v79
	global_store_dwordx4 v[232:233], v[186:189], off offset:256
	s_mov_b32 s98, 0x10000
	v_lshl_add_u64 v[232:233], v[232:233], 0, s[98:99]
	s_nop 0
	global_load_dwordx4 v[186:189], v[174:175], off offset:2304
	s_mov_b32 s98, 0x38000
	v_lshl_add_u64 v[174:175], v[174:175], 0, s[98:99]
	s_waitcnt vmcnt(6)
	v_lshlrev_b32_e32 v198, 16, v190
	v_and_b32_e32 v190, 0xffff0000, v190
	v_lshlrev_b32_e32 v199, 16, v191
	v_and_b32_e32 v191, 0xffff0000, v191
	v_lshlrev_b32_e32 v200, 16, v192
	v_and_b32_e32 v192, 0xffff0000, v192
	v_lshlrev_b32_e32 v201, 16, v193
	v_and_b32_e32 v193, 0xffff0000, v193
	v_mul_f32_e32 v80, v80, v198
	v_mul_f32_e32 v81, v81, v190
	v_mul_f32_e32 v82, v82, v199
	v_mul_f32_e32 v83, v83, v191
	v_mul_f32_e32 v72, v72, v200
	v_mul_f32_e32 v73, v73, v192
	v_mul_f32_e32 v74, v74, v201
	v_mul_f32_e32 v75, v75, v193
	v_cvt_pk_bf16_f32 v190, v80, v81
	v_cvt_pk_bf16_f32 v191, v82, v83
	v_cvt_pk_bf16_f32 v192, v72, v73
	v_cvt_pk_bf16_f32 v193, v74, v75
	global_store_dwordx4 v[232:233], v[190:193], off
	s_nop 0
	global_load_dwordx4 v[190:193], v[174:175], off offset:2048
	s_waitcnt vmcnt(6)
	v_lshlrev_b32_e32 v198, 16, v194
	v_and_b32_e32 v194, 0xffff0000, v194
	v_lshlrev_b32_e32 v199, 16, v195
	v_and_b32_e32 v195, 0xffff0000, v195
	v_lshlrev_b32_e32 v200, 16, v196
	v_and_b32_e32 v196, 0xffff0000, v196
	v_lshlrev_b32_e32 v201, 16, v197
	v_and_b32_e32 v197, 0xffff0000, v197
	v_mul_f32_e32 v68, v68, v198
	v_mul_f32_e32 v69, v69, v194
	v_mul_f32_e32 v70, v70, v199
	v_mul_f32_e32 v71, v71, v195
	v_mul_f32_e32 v64, v64, v200
	v_mul_f32_e32 v65, v65, v196
	v_mul_f32_e32 v66, v66, v201
	v_mul_f32_e32 v67, v67, v197
	v_cvt_pk_bf16_f32 v194, v68, v69
	v_cvt_pk_bf16_f32 v195, v70, v71
	v_cvt_pk_bf16_f32 v196, v64, v65
	v_cvt_pk_bf16_f32 v197, v66, v67
	global_store_dwordx4 v[232:233], v[194:197], off offset:256
	s_mov_b32 s98, 0x50000
	v_lshl_add_u64 v[232:233], v[232:233], 0, s[98:99]
	s_nop 0
	global_load_dwordx4 v[194:197], v[174:175], off offset:2304
	s_mov_b32 s98, 0x38000
	v_lshl_add_u64 v[174:175], v[174:175], 0, s[98:99]
	s_waitcnt vmcnt(6)
	v_lshlrev_b32_e32 v198, 16, v182
	v_and_b32_e32 v182, 0xffff0000, v182
	v_lshlrev_b32_e32 v199, 16, v183
	v_and_b32_e32 v183, 0xffff0000, v183
	v_lshlrev_b32_e32 v200, 16, v184
	v_and_b32_e32 v184, 0xffff0000, v184
	v_lshlrev_b32_e32 v201, 16, v185
	v_and_b32_e32 v185, 0xffff0000, v185
	v_mul_f32_e32 v60, v60, v198
	v_mul_f32_e32 v61, v61, v182
	v_mul_f32_e32 v62, v62, v199
	v_mul_f32_e32 v63, v63, v183
	v_mul_f32_e32 v56, v56, v200
	v_mul_f32_e32 v57, v57, v184
	v_mul_f32_e32 v58, v58, v201
	v_mul_f32_e32 v59, v59, v185
	v_cvt_pk_bf16_f32 v182, v60, v61
	v_cvt_pk_bf16_f32 v183, v62, v63
	v_cvt_pk_bf16_f32 v184, v56, v57
	v_cvt_pk_bf16_f32 v185, v58, v59
	global_store_dwordx4 v[232:233], v[182:185], off
	s_nop 0
	global_load_dwordx4 v[182:185], v[174:175], off offset:2048
	s_waitcnt vmcnt(6)
	v_lshlrev_b32_e32 v198, 16, v186
	v_and_b32_e32 v186, 0xffff0000, v186
	v_lshlrev_b32_e32 v199, 16, v187
	v_and_b32_e32 v187, 0xffff0000, v187
	v_lshlrev_b32_e32 v200, 16, v188
	v_and_b32_e32 v188, 0xffff0000, v188
	v_lshlrev_b32_e32 v201, 16, v189
	v_and_b32_e32 v189, 0xffff0000, v189
	v_mul_f32_e32 v52, v52, v198
	v_mul_f32_e32 v53, v53, v186
	v_mul_f32_e32 v54, v54, v199
	v_mul_f32_e32 v55, v55, v187
	v_mul_f32_e32 v44, v44, v200
	v_mul_f32_e32 v45, v45, v188
	v_mul_f32_e32 v46, v46, v201
	v_mul_f32_e32 v47, v47, v189
	v_cvt_pk_bf16_f32 v186, v52, v53
	v_cvt_pk_bf16_f32 v187, v54, v55
	v_cvt_pk_bf16_f32 v188, v44, v45
	v_cvt_pk_bf16_f32 v189, v46, v47
	global_store_dwordx4 v[232:233], v[186:189], off offset:256
	s_mov_b32 s98, 0x10000
	v_lshl_add_u64 v[232:233], v[232:233], 0, s[98:99]
	s_nop 0
	global_load_dwordx4 v[186:189], v[174:175], off offset:2304
	s_mov_b32 s98, 0x38000
	v_lshl_add_u64 v[174:175], v[174:175], 0, s[98:99]
	s_waitcnt vmcnt(6)
; #define EPI_FENCE() asm volatile("" ::: "memory")
;     __device__ __forceinline__ void operator()(const Acc& acc, const Unit& u, int wr, int wc, int fr, int fq) const {
;         const int row0 = u.pm * BM + wr * 64 + fr, col0 = u.pn * BM + wc * 32 + 8 * fq;
; #pragma unroll
;         for (int ai = 0; ai < 2; ++ai)
; #pragma unroll
;             for (int m = 0; m < 4; ++m) { const int row = row0 + ai * HALF + m * 16;
; #pragma unroll
;                 for (int bj = 0; bj < 2; ++bj) {
;                     const u32x4 gw = *(const u32x4*)(QG + (size_t)row * QGW + gcol0 + col0 + bj * HALF);
;                     float gt[8]; unpack8(gw, gt);
;                     bf16_t* tp = T + (size_t)row * DM + col0 + bj * HALF;
;                     float o[8];
;                     const f32x4 v0 = acc[ai][bj][m][0], v1 = acc[ai][bj][m][1];
; #pragma unroll
;                     for (int j = 0; j < 4; ++j) { o[j] = gt[j] * v0[j]; o[4 + j] = gt[4 + j] * v1[j]; }
;                     if (MODE == 1) { const u32x4 tw = *(const u32x4*)tp; float tv[8]; unpack8(tw, tv);
; #pragma unroll
;                         for (int j = 0; j < 8; ++j) o[j] += tv[j]; }
;                     *(u32x4*)tp = pack8(o); }
;                 EPI_FENCE(); }
;     }
	v_lshlrev_b32_e32 v198, 16, v190
	v_and_b32_e32 v190, 0xffff0000, v190
	v_lshlrev_b32_e32 v199, 16, v191
	v_and_b32_e32 v191, 0xffff0000, v191
	v_lshlrev_b32_e32 v200, 16, v192
	v_and_b32_e32 v192, 0xffff0000, v192
	v_lshlrev_b32_e32 v201, 16, v193
	v_and_b32_e32 v193, 0xffff0000, v193
	v_mul_f32_e32 v48, v48, v198
	v_mul_f32_e32 v49, v49, v190
	v_mul_f32_e32 v50, v50, v199
	v_mul_f32_e32 v51, v51, v191
	v_mul_f32_e32 v40, v40, v200
	v_mul_f32_e32 v41, v41, v192
	v_mul_f32_e32 v42, v42, v201
	v_mul_f32_e32 v43, v43, v193
	v_cvt_pk_bf16_f32 v190, v48, v49
	v_cvt_pk_bf16_f32 v191, v50, v51
	v_cvt_pk_bf16_f32 v192, v40, v41
	v_cvt_pk_bf16_f32 v193, v42, v43
	global_store_dwordx4 v[232:233], v[190:193], off
	s_nop 0
	global_load_dwordx4 v[190:193], v[174:175], off offset:2048
	s_waitcnt vmcnt(6)
	v_lshlrev_b32_e32 v198, 16, v194
	v_and_b32_e32 v194, 0xffff0000, v194
	v_lshlrev_b32_e32 v199, 16, v195
	v_and_b32_e32 v195, 0xffff0000, v195
	v_lshlrev_b32_e32 v200, 16, v196
	v_and_b32_e32 v196, 0xffff0000, v196
	v_lshlrev_b32_e32 v201, 16, v197
	v_and_b32_e32 v197, 0xffff0000, v197
	v_mul_f32_e32 v36, v36, v198
	v_mul_f32_e32 v37, v37, v194
	v_mul_f32_e32 v38, v38, v199
	v_mul_f32_e32 v39, v39, v195
	v_mul_f32_e32 v28, v28, v200
	v_mul_f32_e32 v29, v29, v196
	v_mul_f32_e32 v30, v30, v201
	v_mul_f32_e32 v31, v31, v197
	v_cvt_pk_bf16_f32 v194, v36, v37
	v_cvt_pk_bf16_f32 v195, v38, v39
	v_cvt_pk_bf16_f32 v196, v28, v29
	v_cvt_pk_bf16_f32 v197, v30, v31
	global_store_dwordx4 v[232:233], v[194:197], off offset:256
	s_mov_b32 s98, 0x10000
	v_lshl_add_u64 v[232:233], v[232:233], 0, s[98:99]
	s_nop 0
	global_load_dwordx4 v[194:197], v[174:175], off offset:2304
	s_waitcnt vmcnt(6)
	v_lshlrev_b32_e32 v198, 16, v182
	v_and_b32_e32 v182, 0xffff0000, v182
	v_lshlrev_b32_e32 v199, 16, v183
	v_and_b32_e32 v183, 0xffff0000, v183
	v_lshlrev_b32_e32 v200, 16, v184
	v_and_b32_e32 v184, 0xffff0000, v184
	v_lshlrev_b32_e32 v201, 16, v185
	v_and_b32_e32 v185, 0xffff0000, v185
	v_mul_f32_e32 v32, v32, v198
	v_mul_f32_e32 v33, v33, v182
	v_mul_f32_e32 v34, v34, v199
	v_mul_f32_e32 v35, v35, v183
	v_mul_f32_e32 v24, v24, v200
	v_mul_f32_e32 v25, v25, v184
	v_mul_f32_e32 v26, v26, v201
	v_mul_f32_e32 v27, v27, v185
	v_cvt_pk_bf16_f32 v182, v32, v33
	v_cvt_pk_bf16_f32 v183, v34, v35
	v_cvt_pk_bf16_f32 v184, v24, v25
	v_cvt_pk_bf16_f32 v185, v26, v27
	global_store_dwordx4 v[232:233], v[182:185], off
	s_waitcnt vmcnt(5)
	v_lshlrev_b32_e32 v198, 16, v186
	v_and_b32_e32 v186, 0xffff0000, v186
	v_lshlrev_b32_e32 v199, 16, v187
	v_and_b32_e32 v187, 0xffff0000, v187
	v_lshlrev_b32_e32 v200, 16, v188
	v_and_b32_e32 v188, 0xffff0000, v188
	v_lshlrev_b32_e32 v201, 16, v189
	v_and_b32_e32 v189, 0xffff0000, v189
	v_mul_f32_e32 v20, v20, v198
	v_mul_f32_e32 v21, v21, v186
	v_mul_f32_e32 v22, v22, v199
	v_mul_f32_e32 v23, v23, v187
	v_mul_f32_e32 v12, v12, v200
	v_mul_f32_e32 v13, v13, v188
	v_mul_f32_e32 v14, v14, v201
	v_mul_f32_e32 v15, v15, v189
	v_cvt_pk_bf16_f32 v186, v20, v21
	v_cvt_pk_bf16_f32 v187, v22, v23
	v_cvt_pk_bf16_f32 v188, v12, v13
	v_cvt_pk_bf16_f32 v189, v14, v15
	global_store_dwordx4 v[232:233], v[186:189], off offset:256
	s_mov_b32 s98, 0x10000
	v_lshl_add_u64 v[232:233], v[232:233], 0, s[98:99]
	s_waitcnt vmcnt(4)
	v_lshlrev_b32_e32 v198, 16, v190
	v_and_b32_e32 v190, 0xffff0000, v190
	v_lshlrev_b32_e32 v199, 16, v191
	v_and_b32_e32 v191, 0xffff0000, v191
	v_lshlrev_b32_e32 v200, 16, v192
	v_and_b32_e32 v192, 0xffff0000, v192
	v_lshlrev_b32_e32 v201, 16, v193
	v_and_b32_e32 v193, 0xffff0000, v193
	v_mul_f32_e32 v16, v16, v198
	v_mul_f32_e32 v17, v17, v190
	v_mul_f32_e32 v18, v18, v199
	v_mul_f32_e32 v19, v19, v191
	v_mul_f32_e32 v8, v8, v200
	v_mul_f32_e32 v9, v9, v192
	v_mul_f32_e32 v10, v10, v201
	v_mul_f32_e32 v11, v11, v193
	v_cvt_pk_bf16_f32 v190, v16, v17
	v_cvt_pk_bf16_f32 v191, v18, v19
	v_cvt_pk_bf16_f32 v192, v8, v9
	v_cvt_pk_bf16_f32 v193, v10, v11
	global_store_dwordx4 v[232:233], v[190:193], off
	s_waitcnt vmcnt(3)
	v_lshlrev_b32_e32 v198, 16, v194
	v_and_b32_e32 v194, 0xffff0000, v194
	v_lshlrev_b32_e32 v199, 16, v195
	v_and_b32_e32 v195, 0xffff0000, v195
	v_lshlrev_b32_e32 v200, 16, v196
	v_and_b32_e32 v196, 0xffff0000, v196
	v_lshlrev_b32_e32 v201, 16, v197
	v_and_b32_e32 v197, 0xffff0000, v197
	v_mul_f32_e32 v4, v4, v198
	v_mul_f32_e32 v5, v5, v194
	v_mul_f32_e32 v6, v6, v199
	v_mul_f32_e32 v7, v7, v195
	v_mul_f32_e32 v0, v0, v200
	v_mul_f32_e32 v1, v1, v196
	v_mul_f32_e32 v2, v2, v201
	v_mul_f32_e32 v3, v3, v197
	v_cvt_pk_bf16_f32 v194, v4, v5
	v_cvt_pk_bf16_f32 v195, v6, v7
	v_cvt_pk_bf16_f32 v196, v0, v1
	v_cvt_pk_bf16_f32 v197, v2, v3
	global_store_dwordx4 v[232:233], v[194:197], off offset:256
	s_and_b64 vcc, exec, s[2:3]
	s_mov_b64 s[0:1], -1
	s_cbranch_vccnz .LBB0_715
	s_andn2_b64 vcc, exec, s[20:21]
	s_cbranch_vccnz .LBB0_714
	s_barrier
	s_branch .LBB0_714

;     __device__ __forceinline__ void operator()(const Acc& acc, const Unit& u, int wr, int wc, int fr, int fq) const {
;         const int row0 = u.pm * BM + wr * 64 + fr, col0 = u.pn * BM + wc * 32 + 8 * fq;
; #pragma unroll
;         for (int ai = 0; ai < 2; ++ai)
; #pragma unroll
;             for (int m = 0; m < 4; ++m) { const int row = row0 + ai * HALF + m * 16;
; #pragma unroll
;                 for (int bj = 0; bj < 2; ++bj) {
;                     const u32x4 gw = *(const u32x4*)(QG + (size_t)row * QGW + gcol0 + col0 + bj * HALF);
;                     float gt[8]; unpack8(gw, gt);
;                     bf16_t* tp = T + (size_t)row * DM + col0 + bj * HALF;
;                     float o[8];
;                     const f32x4 v0 = acc[ai][bj][m][0], v1 = acc[ai][bj][m][1];
; #pragma unroll
;                     for (int j = 0; j < 4; ++j) { o[j] = gt[j] * v0[j]; o[4 + j] = gt[4 + j] * v1[j]; }
;                     if (MODE == 1) { const u32x4 tw = *(const u32x4*)tp; float tv[8]; unpack8(tw, tv);
; #pragma unroll
;                         for (int j = 0; j < 8; ++j) o[j] += tv[j]; }
;                     *(u32x4*)tp = pack8(o); }
.LBB0_750:
	v_lshl_or_b32 v144, s55, 8, v152
	v_lshl_add_u32 v146, s54, 8, v150
	v_ashrrev_i32_e32 v145, 31, v144
	v_mov_b64_e32 v[148:149], s[12:13]
	v_mad_i64_i32 v[156:157], s[0:1], v146, s52, v[148:149]
	v_lshlrev_b64 v[144:145], 1, v[144:145]
	v_ashrrev_i32_e32 v147, 31, v146
	v_lshl_add_u64 v[160:161], v[156:157], 0, v[144:145]
	v_lshlrev_b64 v[168:169], 12, v[146:147]
	v_add_co_u32_e32 v156, vcc, 0x2000, v160
	v_lshl_add_u64 v[168:169], s[10:11], 0, v[168:169]
	s_nop 0
	v_addc_co_u32_e32 v157, vcc, 0, v161, vcc
	v_lshl_add_u64 v[172:173], v[168:169], 0, v[144:145]
	v_mov_b32_e32 v224, v172
	v_mov_b32_e32 v225, v173
	s_mov_b32 s99, 0
	global_load_dwordx4 v[176:179], v[156:157], off offset:2048
	global_load_dwordx4 v[192:195], v[172:173], off
	global_load_dwordx4 v[180:183], v[156:157], off offset:2304
	global_load_dwordx4 v[196:199], v[172:173], off offset:256
	s_mov_b32 s98, 0x38000
	v_lshl_add_u64 v[156:157], v[156:157], 0, s[98:99]
	s_mov_b32 s98, 0x10000
	v_lshl_add_u64 v[172:173], v[172:173], 0, s[98:99]
	global_load_dwordx4 v[184:187], v[156:157], off offset:2048
	global_load_dwordx4 v[200:203], v[172:173], off
	global_load_dwordx4 v[188:191], v[156:157], off offset:2304
	global_load_dwordx4 v[204:207], v[172:173], off offset:256
	s_mov_b32 s98, 0x38000
	v_lshl_add_u64 v[156:157], v[156:157], 0, s[98:99]
	s_mov_b32 s98, 0x10000
	v_lshl_add_u64 v[172:173], v[172:173], 0, s[98:99]
	s_waitcnt vmcnt(6)
	v_lshlrev_b32_e32 v208, 16, v176
	v_and_b32_e32 v176, 0xffff0000, v176
	v_lshlrev_b32_e32 v209, 16, v177
	v_and_b32_e32 v177, 0xffff0000, v177
	v_lshlrev_b32_e32 v210, 16, v178
	v_and_b32_e32 v178, 0xffff0000, v178
	v_lshlrev_b32_e32 v211, 16, v179
	v_and_b32_e32 v179, 0xffff0000, v179
	v_lshlrev_b32_e32 v212, 16, v192
	v_and_b32_e32 v192, 0xffff0000, v192
	v_lshlrev_b32_e32 v213, 16, v193
	v_and_b32_e32 v193, 0xffff0000, v193
	v_lshlrev_b32_e32 v214, 16, v194
	v_and_b32_e32 v194, 0xffff0000, v194
	v_lshlrev_b32_e32 v215, 16, v195
	v_and_b32_e32 v195, 0xffff0000, v195
	v_fmac_f32_e32 v212, v124, v208
	v_fmac_f32_e32 v192, v125, v176
	v_fmac_f32_e32 v213, v126, v209
	v_fmac_f32_e32 v193, v127, v177
	v_fmac_f32_e32 v214, v120, v210
	v_fmac_f32_e32 v194, v121, v178
	v_fmac_f32_e32 v215, v122, v211
	v_fmac_f32_e32 v195, v123, v179
	v_cvt_pk_bf16_f32 v176, v212, v192
	v_cvt_pk_bf16_f32 v177, v213, v193
	v_cvt_pk_bf16_f32 v178, v214, v194
	v_cvt_pk_bf16_f32 v179, v215, v195
	global_store_dwordx4 v[224:225], v[176:179], off
	s_nop 0
	global_load_dwordx4 v[176:179], v[156:157], off offset:2048
	global_load_dwordx4 v[192:195], v[172:173], off
	s_waitcnt vmcnt(7)
	v_lshlrev_b32_e32 v208, 16, v180
	v_and_b32_e32 v180, 0xffff0000, v180
	v_lshlrev_b32_e32 v209, 16, v181
	v_and_b32_e32 v181, 0xffff0000, v181
	v_lshlrev_b32_e32 v210, 16, v182
	v_and_b32_e32 v182, 0xffff0000, v182
	v_lshlrev_b32_e32 v211, 16, v183
	v_and_b32_e32 v183, 0xffff0000, v183
	v_lshlrev_b32_e32 v212, 16, v196
	v_and_b32_e32 v196, 0xffff0000, v196
	v_lshlrev_b32_e32 v213, 16, v197
	v_and_b32_e32 v197, 0xffff0000, v197
	v_lshlrev_b32_e32 v214, 16, v198
	v_and_b32_e32 v198, 0xffff0000, v198
	v_lshlrev_b32_e32 v215, 16, v199
	v_and_b32_e32 v199, 0xffff0000, v199
	v_fmac_f32_e32 v212, v116, v208
	v_fmac_f32_e32 v196, v117, v180
	v_fmac_f32_e32 v213, v118, v209
	v_fmac_f32_e32 v197, v119, v181
	v_fmac_f32_e32 v214, v112, v210
	v_fmac_f32_e32 v198, v113, v182
	v_fmac_f32_e32 v215, v114, v211
	v_fmac_f32_e32 v199, v115, v183
	v_cvt_pk_bf16_f32 v180, v212, v196
	v_cvt_pk_bf16_f32 v181, v213, v197
	v_cvt_pk_bf16_f32 v182, v214, v198
	v_cvt_pk_bf16_f32 v183, v215, v199
	global_store_dwordx4 v[224:225], v[180:183], off offset:256
	s_mov_b32 s98, 0x10000
	v_lshl_add_u64 v[224:225], v[224:225], 0, s[98:99]
	s_nop 0
	global_load_dwordx4 v[180:183], v[156:157], off offset:2304
	global_load_dwordx4 v[196:199], v[172:173], off offset:256
	s_mov_b32 s98, 0x38000
	v_lshl_add_u64 v[156:157], v[156:157], 0, s[98:99]
	s_mov_b32 s98, 0x10000
	v_lshl_add_u64 v[172:173], v[172:173], 0, s[98:99]
	s_waitcnt vmcnt(8)
	v_lshlrev_b32_e32 v208, 16, v184
	v_and_b32_e32 v184, 0xffff0000, v184
	v_lshlrev_b32_e32 v209, 16, v185
	v_and_b32_e32 v185, 0xffff0000, v185
	v_lshlrev_b32_e32 v210, 16, v186
	v_and_b32_e32 v186, 0xffff0000, v186
	v_lshlrev_b32_e32 v211, 16, v187
	v_and_b32_e32 v187, 0xffff0000, v187
	v_lshlrev_b32_e32 v212, 16, v200
	v_and_b32_e32 v200, 0xffff0000, v200
	v_lshlrev_b32_e32 v213, 16, v201
	v_and_b32_e32 v201, 0xffff0000, v201
	v_lshlrev_b32_e32 v214, 16, v202
	v_and_b32_e32 v202, 0xffff0000, v202
	v_lshlrev_b32_e32 v215, 16, v203
	v_and_b32_e32 v203, 0xffff0000, v203
	v_fmac_f32_e32 v212, v108, v208
	v_fmac_f32_e32 v200, v109, v184
	v_fmac_f32_e32 v213, v110, v209
	v_fmac_f32_e32 v201, v111, v185
	v_fmac_f32_e32 v214, v104, v210
	v_fmac_f32_e32 v202, v105, v186
	v_fmac_f32_e32 v215, v106, v211
	v_fmac_f32_e32 v203, v107, v187
	v_cvt_pk_bf16_f32 v184, v212, v200
	v_cvt_pk_bf16_f32 v185, v213, v201
	v_cvt_pk_bf16_f32 v186, v214, v202
	v_cvt_pk_bf16_f32 v187, v215, v203
	global_store_dwordx4 v[224:225], v[184:187], off
	s_nop 0
	global_load_dwordx4 v[184:187], v[156:157], off offset:2048
	global_load_dwordx4 v[200:203], v[172:173], off
	s_waitcnt vmcnt(9)
;     __device__ __forceinline__ void operator()(const Acc& acc, const Unit& u, int wr, int wc, int fr, int fq) const {
;     ...
;             for (int m = 0; m < 4; ++m) { const int row = row0 + ai * HALF + m * 16;
; #pragma unroll
;                 for (int bj = 0; bj < 2; ++bj) {
;                     const u32x4 gw = *(const u32x4*)(QG + (size_t)row * QGW + gcol0 + col0 + bj * HALF);
;                     float gt[8]; unpack8(gw, gt);
;                     bf16_t* tp = T + (size_t)row * DM + col0 + bj * HALF;
;                     float o[8];
;                     const f32x4 v0 = acc[ai][bj][m][0], v1 = acc[ai][bj][m][1];
; #pragma unroll
;                     for (int j = 0; j < 4; ++j) { o[j] = gt[j] * v0[j]; o[4 + j] = gt[4 + j] * v1[j]; }
;                     if (MODE == 1) { const u32x4 tw = *(const u32x4*)tp; float tv[8]; unpack8(tw, tv);
; #pragma unroll
;                         for (int j = 0; j < 8; ++j) o[j] += tv[j]; }
;                     *(u32x4*)tp = pack8(o); }
	v_lshlrev_b32_e32 v208, 16, v188
	v_and_b32_e32 v188, 0xffff0000, v188
	v_lshlrev_b32_e32 v209, 16, v189
	v_and_b32_e32 v189, 0xffff0000, v189
	v_lshlrev_b32_e32 v210, 16, v190
	v_and_b32_e32 v190, 0xffff0000, v190
	v_lshlrev_b32_e32 v211, 16, v191
	v_and_b32_e32 v191, 0xffff0000, v191
	v_lshlrev_b32_e32 v212, 16, v204
	v_and_b32_e32 v204, 0xffff0000, v204
	v_lshlrev_b32_e32 v213, 16, v205
	v_and_b32_e32 v205, 0xffff0000, v205
	v_lshlrev_b32_e32 v214, 16, v206
	v_and_b32_e32 v206, 0xffff0000, v206
	v_lshlrev_b32_e32 v215, 16, v207
	v_and_b32_e32 v207, 0xffff0000, v207
	v_fmac_f32_e32 v212, v100, v208
	v_fmac_f32_e32 v204, v101, v188
	v_fmac_f32_e32 v213, v102, v209
	v_fmac_f32_e32 v205, v103, v189
	v_fmac_f32_e32 v214, v96, v210
	v_fmac_f32_e32 v206, v97, v190
	v_fmac_f32_e32 v215, v98, v211
	v_fmac_f32_e32 v207, v99, v191
	v_cvt_pk_bf16_f32 v188, v212, v204
	v_cvt_pk_bf16_f32 v189, v213, v205
	v_cvt_pk_bf16_f32 v190, v214, v206
	v_cvt_pk_bf16_f32 v191, v215, v207
	global_store_dwordx4 v[224:225], v[188:191], off offset:256
	s_mov_b32 s98, 0x10000
	v_lshl_add_u64 v[224:225], v[224:225], 0, s[98:99]
	s_nop 0
	global_load_dwordx4 v[188:191], v[156:157], off offset:2304
	global_load_dwordx4 v[204:207], v[172:173], off offset:256
	s_mov_b32 s98, 0x118000
	v_lshl_add_u64 v[156:157], v[156:157], 0, s[98:99]
	s_mov_b32 s98, 0x50000
	v_lshl_add_u64 v[172:173], v[172:173], 0, s[98:99]
	s_waitcnt vmcnt(9)
	v_lshlrev_b32_e32 v208, 16, v176
	v_and_b32_e32 v176, 0xffff0000, v176
	v_lshlrev_b32_e32 v209, 16, v177
	v_and_b32_e32 v177, 0xffff0000, v177
	v_lshlrev_b32_e32 v210, 16, v178
	v_and_b32_e32 v178, 0xffff0000, v178
	v_lshlrev_b32_e32 v211, 16, v179
	v_and_b32_e32 v179, 0xffff0000, v179
	v_lshlrev_b32_e32 v212, 16, v192
	v_and_b32_e32 v192, 0xffff0000, v192
	v_lshlrev_b32_e32 v213, 16, v193
	v_and_b32_e32 v193, 0xffff0000, v193
	v_lshlrev_b32_e32 v214, 16, v194
	v_and_b32_e32 v194, 0xffff0000, v194
	v_lshlrev_b32_e32 v215, 16, v195
	v_and_b32_e32 v195, 0xffff0000, v195
	v_fmac_f32_e32 v212, v92, v208
	v_fmac_f32_e32 v192, v93, v176
	v_fmac_f32_e32 v213, v94, v209
	v_fmac_f32_e32 v193, v95, v177
	v_fmac_f32_e32 v214, v88, v210
	v_fmac_f32_e32 v194, v89, v178
	v_fmac_f32_e32 v215, v90, v211
	v_fmac_f32_e32 v195, v91, v179
	v_cvt_pk_bf16_f32 v176, v212, v192
	v_cvt_pk_bf16_f32 v177, v213, v193
	v_cvt_pk_bf16_f32 v178, v214, v194
	v_cvt_pk_bf16_f32 v179, v215, v195
	global_store_dwordx4 v[224:225], v[176:179], off
	s_nop 0
	global_load_dwordx4 v[176:179], v[156:157], off offset:2048
	global_load_dwordx4 v[192:195], v[172:173], off
	s_waitcnt vmcnt(9)
	v_lshlrev_b32_e32 v208, 16, v180
	v_and_b32_e32 v180, 0xffff0000, v180
	v_lshlrev_b32_e32 v209, 16, v181
	v_and_b32_e32 v181, 0xffff0000, v181
	v_lshlrev_b32_e32 v210, 16, v182
	v_and_b32_e32 v182, 0xffff0000, v182
	v_lshlrev_b32_e32 v211, 16, v183
	v_and_b32_e32 v183, 0xffff0000, v183
	v_lshlrev_b32_e32 v212, 16, v196
	v_and_b32_e32 v196, 0xffff0000, v196
	v_lshlrev_b32_e32 v213, 16, v197
	v_and_b32_e32 v197, 0xffff0000, v197
	v_lshlrev_b32_e32 v214, 16, v198
	v_and_b32_e32 v198, 0xffff0000, v198
	v_lshlrev_b32_e32 v215, 16, v199
	v_and_b32_e32 v199, 0xffff0000, v199
	v_fmac_f32_e32 v212, v84, v208
	v_fmac_f32_e32 v196, v85, v180
	v_fmac_f32_e32 v213, v86, v209
	v_fmac_f32_e32 v197, v87, v181
	v_fmac_f32_e32 v214, v80, v210
	v_fmac_f32_e32 v198, v81, v182
	v_fmac_f32_e32 v215, v82, v211
	v_fmac_f32_e32 v199, v83, v183
	v_cvt_pk_bf16_f32 v180, v212, v196
	v_cvt_pk_bf16_f32 v181, v213, v197
	v_cvt_pk_bf16_f32 v182, v214, v198
	v_cvt_pk_bf16_f32 v183, v215, v199
	global_store_dwordx4 v[224:225], v[180:183], off offset:256
	s_mov_b32 s98, 0x10000
	v_lshl_add_u64 v[224:225], v[224:225], 0, s[98:99]
	s_nop 0
	global_load_dwordx4 v[180:183], v[156:157], off offset:2304
	global_load_dwordx4 v[196:199], v[172:173], off offset:256
	s_mov_b32 s98, 0x38000
	v_lshl_add_u64 v[156:157], v[156:157], 0, s[98:99]
	s_mov_b32 s98, 0x10000
	v_lshl_add_u64 v[172:173], v[172:173], 0, s[98:99]
	s_waitcnt vmcnt(9)
	v_lshlrev_b32_e32 v208, 16, v184
	v_and_b32_e32 v184, 0xffff0000, v184
	v_lshlrev_b32_e32 v209, 16, v185
	v_and_b32_e32 v185, 0xffff0000, v185
	v_lshlrev_b32_e32 v210, 16, v186
	v_and_b32_e32 v186, 0xffff0000, v186
	v_lshlrev_b32_e32 v211, 16, v187
	v_and_b32_e32 v187, 0xffff0000, v187
	v_lshlrev_b32_e32 v212, 16, v200
	v_and_b32_e32 v200, 0xffff0000, v200
	v_lshlrev_b32_e32 v213, 16, v201
	v_and_b32_e32 v201, 0xffff0000, v201
	v_lshlrev_b32_e32 v214, 16, v202
	v_and_b32_e32 v202, 0xffff0000, v202
	v_lshlrev_b32_e32 v215, 16, v203
	v_and_b32_e32 v203, 0xffff0000, v203
	v_fmac_f32_e32 v212, v76, v208
	v_fmac_f32_e32 v200, v77, v184
	v_fmac_f32_e32 v213, v78, v209
	v_fmac_f32_e32 v201, v79, v185
	v_fmac_f32_e32 v214, v72, v210
	v_fmac_f32_e32 v202, v73, v186
	v_fmac_f32_e32 v215, v74, v211
	v_fmac_f32_e32 v203, v75, v187
	v_cvt_pk_bf16_f32 v184, v212, v200
	v_cvt_pk_bf16_f32 v185, v213, v201
	v_cvt_pk_bf16_f32 v186, v214, v202
	v_cvt_pk_bf16_f32 v187, v215, v203
	global_store_dwordx4 v[224:225], v[184:187], off
	s_nop 0
	global_load_dwordx4 v[184:187], v[156:157], off offset:2048
	global_load_dwordx4 v[200:203], v[172:173], off
	s_waitcnt vmcnt(9)
;     __device__ __forceinline__ void operator()(const Acc& acc, const Unit& u, int wr, int wc, int fr, int fq) const {
;     ...
;             for (int m = 0; m < 4; ++m) { const int row = row0 + ai * HALF + m * 16;
; #pragma unroll
;                 for (int bj = 0; bj < 2; ++bj) {
;                     const u32x4 gw = *(const u32x4*)(QG + (size_t)row * QGW + gcol0 + col0 + bj * HALF);
;                     float gt[8]; unpack8(gw, gt);
;                     bf16_t* tp = T + (size_t)row * DM + col0 + bj * HALF;
;                     float o[8];
;                     const f32x4 v0 = acc[ai][bj][m][0], v1 = acc[ai][bj][m][1];
; #pragma unroll
;                     for (int j = 0; j < 4; ++j) { o[j] = gt[j] * v0[j]; o[4 + j] = gt[4 + j] * v1[j]; }
;                     if (MODE == 1) { const u32x4 tw = *(const u32x4*)tp; float tv[8]; unpack8(tw, tv);
; #pragma unroll
;                         for (int j = 0; j < 8; ++j) o[j] += tv[j]; }
;                     *(u32x4*)tp = pack8(o); }
	v_lshlrev_b32_e32 v208, 16, v188
	v_and_b32_e32 v188, 0xffff0000, v188
	v_lshlrev_b32_e32 v209, 16, v189
	v_and_b32_e32 v189, 0xffff0000, v189
	v_lshlrev_b32_e32 v210, 16, v190
	v_and_b32_e32 v190, 0xffff0000, v190
	v_lshlrev_b32_e32 v211, 16, v191
	v_and_b32_e32 v191, 0xffff0000, v191
	v_lshlrev_b32_e32 v212, 16, v204
	v_and_b32_e32 v204, 0xffff0000, v204
	v_lshlrev_b32_e32 v213, 16, v205
	v_and_b32_e32 v205, 0xffff0000, v205
	v_lshlrev_b32_e32 v214, 16, v206
	v_and_b32_e32 v206, 0xffff0000, v206
	v_lshlrev_b32_e32 v215, 16, v207
	v_and_b32_e32 v207, 0xffff0000, v207
	v_fmac_f32_e32 v212, v68, v208
	v_fmac_f32_e32 v204, v69, v188
	v_fmac_f32_e32 v213, v70, v209
	v_fmac_f32_e32 v205, v71, v189
	v_fmac_f32_e32 v214, v64, v210
	v_fmac_f32_e32 v206, v65, v190
	v_fmac_f32_e32 v215, v66, v211
	v_fmac_f32_e32 v207, v67, v191
	v_cvt_pk_bf16_f32 v188, v212, v204
	v_cvt_pk_bf16_f32 v189, v213, v205
	v_cvt_pk_bf16_f32 v190, v214, v206
	v_cvt_pk_bf16_f32 v191, v215, v207
	global_store_dwordx4 v[224:225], v[188:191], off offset:256
	s_mov_b32 s98, 0x50000
	v_lshl_add_u64 v[224:225], v[224:225], 0, s[98:99]
	s_nop 0
	global_load_dwordx4 v[188:191], v[156:157], off offset:2304
	global_load_dwordx4 v[204:207], v[172:173], off offset:256
	s_mov_b32 s98, 0x38000
	v_lshl_add_u64 v[156:157], v[156:157], 0, s[98:99]
	s_mov_b32 s98, 0x10000
	v_lshl_add_u64 v[172:173], v[172:173], 0, s[98:99]
	s_waitcnt vmcnt(9)
	v_lshlrev_b32_e32 v208, 16, v176
	v_and_b32_e32 v176, 0xffff0000, v176
	v_lshlrev_b32_e32 v209, 16, v177
	v_and_b32_e32 v177, 0xffff0000, v177
	v_lshlrev_b32_e32 v210, 16, v178
	v_and_b32_e32 v178, 0xffff0000, v178
	v_lshlrev_b32_e32 v211, 16, v179
	v_and_b32_e32 v179, 0xffff0000, v179
	v_lshlrev_b32_e32 v212, 16, v192
	v_and_b32_e32 v192, 0xffff0000, v192
	v_lshlrev_b32_e32 v213, 16, v193
	v_and_b32_e32 v193, 0xffff0000, v193
	v_lshlrev_b32_e32 v214, 16, v194
	v_and_b32_e32 v194, 0xffff0000, v194
	v_lshlrev_b32_e32 v215, 16, v195
	v_and_b32_e32 v195, 0xffff0000, v195
	v_fmac_f32_e32 v212, v60, v208
	v_fmac_f32_e32 v192, v61, v176
	v_fmac_f32_e32 v213, v62, v209
	v_fmac_f32_e32 v193, v63, v177
	v_fmac_f32_e32 v214, v56, v210
	v_fmac_f32_e32 v194, v57, v178
	v_fmac_f32_e32 v215, v58, v211
	v_fmac_f32_e32 v195, v59, v179
	v_cvt_pk_bf16_f32 v176, v212, v192
	v_cvt_pk_bf16_f32 v177, v213, v193
	v_cvt_pk_bf16_f32 v178, v214, v194
	v_cvt_pk_bf16_f32 v179, v215, v195
	global_store_dwordx4 v[224:225], v[176:179], off
	s_nop 0
	global_load_dwordx4 v[176:179], v[156:157], off offset:2048
	global_load_dwordx4 v[192:195], v[172:173], off
	s_waitcnt vmcnt(9)
	v_lshlrev_b32_e32 v208, 16, v180
	v_and_b32_e32 v180, 0xffff0000, v180
	v_lshlrev_b32_e32 v209, 16, v181
	v_and_b32_e32 v181, 0xffff0000, v181
	v_lshlrev_b32_e32 v210, 16, v182
	v_and_b32_e32 v182, 0xffff0000, v182
	v_lshlrev_b32_e32 v211, 16, v183
	v_and_b32_e32 v183, 0xffff0000, v183
	v_lshlrev_b32_e32 v212, 16, v196
	v_and_b32_e32 v196, 0xffff0000, v196
	v_lshlrev_b32_e32 v213, 16, v197
	v_and_b32_e32 v197, 0xffff0000, v197
	v_lshlrev_b32_e32 v214, 16, v198
	v_and_b32_e32 v198, 0xffff0000, v198
	v_lshlrev_b32_e32 v215, 16, v199
	v_and_b32_e32 v199, 0xffff0000, v199
	v_fmac_f32_e32 v212, v52, v208
	v_fmac_f32_e32 v196, v53, v180
	v_fmac_f32_e32 v213, v54, v209
	v_fmac_f32_e32 v197, v55, v181
	v_fmac_f32_e32 v214, v48, v210
	v_fmac_f32_e32 v198, v49, v182
	v_fmac_f32_e32 v215, v50, v211
	v_fmac_f32_e32 v199, v51, v183
	v_cvt_pk_bf16_f32 v180, v212, v196
	v_cvt_pk_bf16_f32 v181, v213, v197
	v_cvt_pk_bf16_f32 v182, v214, v198
	v_cvt_pk_bf16_f32 v183, v215, v199
	global_store_dwordx4 v[224:225], v[180:183], off offset:256
	s_mov_b32 s98, 0x10000
	v_lshl_add_u64 v[224:225], v[224:225], 0, s[98:99]
	s_nop 0
	global_load_dwordx4 v[180:183], v[156:157], off offset:2304
	global_load_dwordx4 v[196:199], v[172:173], off offset:256
	s_mov_b32 s98, 0x38000
	v_lshl_add_u64 v[156:157], v[156:157], 0, s[98:99]
	s_mov_b32 s98, 0x10000
	v_lshl_add_u64 v[172:173], v[172:173], 0, s[98:99]
	s_waitcnt vmcnt(9)
	v_lshlrev_b32_e32 v208, 16, v184
	v_and_b32_e32 v184, 0xffff0000, v184
	v_lshlrev_b32_e32 v209, 16, v185
	v_and_b32_e32 v185, 0xffff0000, v185
	v_lshlrev_b32_e32 v210, 16, v186
	v_and_b32_e32 v186, 0xffff0000, v186
	v_lshlrev_b32_e32 v211, 16, v187
	v_and_b32_e32 v187, 0xffff0000, v187
	v_lshlrev_b32_e32 v212, 16, v200
	v_and_b32_e32 v200, 0xffff0000, v200
	v_lshlrev_b32_e32 v213, 16, v201
	v_and_b32_e32 v201, 0xffff0000, v201
	v_lshlrev_b32_e32 v214, 16, v202
	v_and_b32_e32 v202, 0xffff0000, v202
	v_lshlrev_b32_e32 v215, 16, v203
	v_and_b32_e32 v203, 0xffff0000, v203
	v_fmac_f32_e32 v212, v44, v208
	v_fmac_f32_e32 v200, v45, v184
	v_fmac_f32_e32 v213, v46, v209
	v_fmac_f32_e32 v201, v47, v185
	v_fmac_f32_e32 v214, v40, v210
	v_fmac_f32_e32 v202, v41, v186
	v_fmac_f32_e32 v215, v42, v211
	v_fmac_f32_e32 v203, v43, v187
	v_cvt_pk_bf16_f32 v184, v212, v200
	v_cvt_pk_bf16_f32 v185, v213, v201
	v_cvt_pk_bf16_f32 v186, v214, v202
	v_cvt_pk_bf16_f32 v187, v215, v203
	global_store_dwordx4 v[224:225], v[184:187], off
	s_nop 0
	global_load_dwordx4 v[184:187], v[156:157], off offset:2048
	global_load_dwordx4 v[200:203], v[172:173], off
	s_waitcnt vmcnt(9)
; #define EPI_FENCE() asm volatile("" ::: "memory")
;     __device__ __forceinline__ void operator()(const Acc& acc, const Unit& u, int wr, int wc, int fr, int fq) const {
;     ...
;             for (int m = 0; m < 4; ++m) { const int row = row0 + ai * HALF + m * 16;
; #pragma unroll
;                 for (int bj = 0; bj < 2; ++bj) {
;                     const u32x4 gw = *(const u32x4*)(QG + (size_t)row * QGW + gcol0 + col0 + bj * HALF);
;                     float gt[8]; unpack8(gw, gt);
;                     bf16_t* tp = T + (size_t)row * DM + col0 + bj * HALF;
;                     float o[8];
;                     const f32x4 v0 = acc[ai][bj][m][0], v1 = acc[ai][bj][m][1];
; #pragma unroll
;                     for (int j = 0; j < 4; ++j) { o[j] = gt[j] * v0[j]; o[4 + j] = gt[4 + j] * v1[j]; }
;                     if (MODE == 1) { const u32x4 tw = *(const u32x4*)tp; float tv[8]; unpack8(tw, tv);
; #pragma unroll
;                         for (int j = 0; j < 8; ++j) o[j] += tv[j]; }
;                     *(u32x4*)tp = pack8(o); }
;                 EPI_FENCE(); }
	v_lshlrev_b32_e32 v208, 16, v188
	v_and_b32_e32 v188, 0xffff0000, v188
	v_lshlrev_b32_e32 v209, 16, v189
	v_and_b32_e32 v189, 0xffff0000, v189
	v_lshlrev_b32_e32 v210, 16, v190
	v_and_b32_e32 v190, 0xffff0000, v190
	v_lshlrev_b32_e32 v211, 16, v191
	v_and_b32_e32 v191, 0xffff0000, v191
	v_lshlrev_b32_e32 v212, 16, v204
	v_and_b32_e32 v204, 0xffff0000, v204
	v_lshlrev_b32_e32 v213, 16, v205
	v_and_b32_e32 v205, 0xffff0000, v205
	v_lshlrev_b32_e32 v214, 16, v206
	v_and_b32_e32 v206, 0xffff0000, v206
	v_lshlrev_b32_e32 v215, 16, v207
	v_and_b32_e32 v207, 0xffff0000, v207
	v_fmac_f32_e32 v212, v36, v208
	v_fmac_f32_e32 v204, v37, v188
	v_fmac_f32_e32 v213, v38, v209
	v_fmac_f32_e32 v205, v39, v189
	v_fmac_f32_e32 v214, v32, v210
	v_fmac_f32_e32 v206, v33, v190
	v_fmac_f32_e32 v215, v34, v211
	v_fmac_f32_e32 v207, v35, v191
	v_cvt_pk_bf16_f32 v188, v212, v204
	v_cvt_pk_bf16_f32 v189, v213, v205
	v_cvt_pk_bf16_f32 v190, v214, v206
	v_cvt_pk_bf16_f32 v191, v215, v207
	global_store_dwordx4 v[224:225], v[188:191], off offset:256
	s_mov_b32 s98, 0x10000
	v_lshl_add_u64 v[224:225], v[224:225], 0, s[98:99]
	s_nop 0
	global_load_dwordx4 v[188:191], v[156:157], off offset:2304
	global_load_dwordx4 v[204:207], v[172:173], off offset:256
	s_waitcnt vmcnt(9)
	v_lshlrev_b32_e32 v208, 16, v176
	v_and_b32_e32 v176, 0xffff0000, v176
	v_lshlrev_b32_e32 v209, 16, v177
	v_and_b32_e32 v177, 0xffff0000, v177
	v_lshlrev_b32_e32 v210, 16, v178
	v_and_b32_e32 v178, 0xffff0000, v178
	v_lshlrev_b32_e32 v211, 16, v179
	v_and_b32_e32 v179, 0xffff0000, v179
	v_lshlrev_b32_e32 v212, 16, v192
	v_and_b32_e32 v192, 0xffff0000, v192
	v_lshlrev_b32_e32 v213, 16, v193
	v_and_b32_e32 v193, 0xffff0000, v193
	v_lshlrev_b32_e32 v214, 16, v194
	v_and_b32_e32 v194, 0xffff0000, v194
	v_lshlrev_b32_e32 v215, 16, v195
	v_and_b32_e32 v195, 0xffff0000, v195
	v_fmac_f32_e32 v212, v28, v208
	v_fmac_f32_e32 v192, v29, v176
	v_fmac_f32_e32 v213, v30, v209
	v_fmac_f32_e32 v193, v31, v177
	v_fmac_f32_e32 v214, v24, v210
	v_fmac_f32_e32 v194, v25, v178
	v_fmac_f32_e32 v215, v26, v211
	v_fmac_f32_e32 v195, v27, v179
	v_cvt_pk_bf16_f32 v176, v212, v192
	v_cvt_pk_bf16_f32 v177, v213, v193
	v_cvt_pk_bf16_f32 v178, v214, v194
	v_cvt_pk_bf16_f32 v179, v215, v195
	global_store_dwordx4 v[224:225], v[176:179], off
	s_waitcnt vmcnt(7)
	v_lshlrev_b32_e32 v208, 16, v180
	v_and_b32_e32 v180, 0xffff0000, v180
	v_lshlrev_b32_e32 v209, 16, v181
	v_and_b32_e32 v181, 0xffff0000, v181
	v_lshlrev_b32_e32 v210, 16, v182
	v_and_b32_e32 v182, 0xffff0000, v182
	v_lshlrev_b32_e32 v211, 16, v183
	v_and_b32_e32 v183, 0xffff0000, v183
	v_lshlrev_b32_e32 v212, 16, v196
	v_and_b32_e32 v196, 0xffff0000, v196
	v_lshlrev_b32_e32 v213, 16, v197
	v_and_b32_e32 v197, 0xffff0000, v197
	v_lshlrev_b32_e32 v214, 16, v198
	v_and_b32_e32 v198, 0xffff0000, v198
	v_lshlrev_b32_e32 v215, 16, v199
	v_and_b32_e32 v199, 0xffff0000, v199
	v_fmac_f32_e32 v212, v20, v208
	v_fmac_f32_e32 v196, v21, v180
	v_fmac_f32_e32 v213, v22, v209
	v_fmac_f32_e32 v197, v23, v181
	v_fmac_f32_e32 v214, v16, v210
	v_fmac_f32_e32 v198, v17, v182
	v_fmac_f32_e32 v215, v18, v211
	v_fmac_f32_e32 v199, v19, v183
	v_cvt_pk_bf16_f32 v180, v212, v196
	v_cvt_pk_bf16_f32 v181, v213, v197
	v_cvt_pk_bf16_f32 v182, v214, v198
	v_cvt_pk_bf16_f32 v183, v215, v199
	global_store_dwordx4 v[224:225], v[180:183], off offset:256
	s_mov_b32 s98, 0x10000
	v_lshl_add_u64 v[224:225], v[224:225], 0, s[98:99]
	s_waitcnt vmcnt(5)
	v_lshlrev_b32_e32 v208, 16, v184
	v_and_b32_e32 v184, 0xffff0000, v184
	v_lshlrev_b32_e32 v209, 16, v185
	v_and_b32_e32 v185, 0xffff0000, v185
	v_lshlrev_b32_e32 v210, 16, v186
	v_and_b32_e32 v186, 0xffff0000, v186
	v_lshlrev_b32_e32 v211, 16, v187
	v_and_b32_e32 v187, 0xffff0000, v187
	v_lshlrev_b32_e32 v212, 16, v200
	v_and_b32_e32 v200, 0xffff0000, v200
	v_lshlrev_b32_e32 v213, 16, v201
	v_and_b32_e32 v201, 0xffff0000, v201
	v_lshlrev_b32_e32 v214, 16, v202
	v_and_b32_e32 v202, 0xffff0000, v202
	v_lshlrev_b32_e32 v215, 16, v203
	v_and_b32_e32 v203, 0xffff0000, v203
	v_fmac_f32_e32 v212, v12, v208
	v_fmac_f32_e32 v200, v13, v184
	v_fmac_f32_e32 v213, v14, v209
	v_fmac_f32_e32 v201, v15, v185
	v_fmac_f32_e32 v214, v8, v210
	v_fmac_f32_e32 v202, v9, v186
	v_fmac_f32_e32 v215, v10, v211
	v_fmac_f32_e32 v203, v11, v187
	v_cvt_pk_bf16_f32 v184, v212, v200
	v_cvt_pk_bf16_f32 v185, v213, v201
	v_cvt_pk_bf16_f32 v186, v214, v202
	v_cvt_pk_bf16_f32 v187, v215, v203
	global_store_dwordx4 v[224:225], v[184:187], off
	s_waitcnt vmcnt(3)
	v_lshlrev_b32_e32 v208, 16, v188
	v_and_b32_e32 v188, 0xffff0000, v188
	v_lshlrev_b32_e32 v209, 16, v189
	v_and_b32_e32 v189, 0xffff0000, v189
	v_lshlrev_b32_e32 v210, 16, v190
	v_and_b32_e32 v190, 0xffff0000, v190
	v_lshlrev_b32_e32 v211, 16, v191
	v_and_b32_e32 v191, 0xffff0000, v191
	v_lshlrev_b32_e32 v212, 16, v204
	v_and_b32_e32 v204, 0xffff0000, v204
	v_lshlrev_b32_e32 v213, 16, v205
	v_and_b32_e32 v205, 0xffff0000, v205
	v_lshlrev_b32_e32 v214, 16, v206
	v_and_b32_e32 v206, 0xffff0000, v206
	v_lshlrev_b32_e32 v215, 16, v207
	v_and_b32_e32 v207, 0xffff0000, v207
	v_fmac_f32_e32 v212, v4, v208
	v_fmac_f32_e32 v204, v5, v188
	v_fmac_f32_e32 v213, v6, v209
	v_fmac_f32_e32 v205, v7, v189
	v_fmac_f32_e32 v214, v0, v210
	v_fmac_f32_e32 v206, v1, v190
	v_fmac_f32_e32 v215, v2, v211
	v_fmac_f32_e32 v207, v3, v191
	v_cvt_pk_bf16_f32 v188, v212, v204
	v_cvt_pk_bf16_f32 v189, v213, v205
	v_cvt_pk_bf16_f32 v190, v214, v206
	v_cvt_pk_bf16_f32 v191, v215, v207
	global_store_dwordx4 v[224:225], v[188:191], off offset:256
	s_mov_b64 s[0:1], -1
	s_and_b64 vcc, exec, s[2:3]
	s_cbranch_vccnz .LBB0_737
	s_andn2_b64 vcc, exec, s[8:9]
	s_cbranch_vccnz .LBB0_736
	s_barrier
	s_branch .LBB0_736
